# grid barrier trimming: early acquire invalidate (as v27) + poll loop s_sleep 2 -> s_sleep 0 (stacked on v17 + diff loop head pinned)
# speedup vs baseline: 1.0066x; 1.0066x over previous
; DI void grid_barrier(int wv, unsigned* bar_, unsigned k, LAS unsigned* stash) {
;     ...
;         while (__hip_atomic_load(bar + 64 * 34, __ATOMIC_RELAXED, __HIP_MEMORY_SCOPE_AGENT) < k) __builtin_amdgcn_s_sleep(2);
;         __builtin_amdgcn_fence(__ATOMIC_ACQUIRE, "agent");
;         asm volatile("s_waitcnt vmcnt(0)" ::: "memory");
.LBB0_43:
	s_sleep 0
	global_load_dword v3, v2, s[8:9] sc1
	s_waitcnt vmcnt(0)
	v_cmp_eq_u32_e32 vcc, 0, v3
	s_cbranch_vccnz .LBB0_43

; DI void grid_barrier(int wv, unsigned* bar_, unsigned k, LAS unsigned* stash) {
;     ...
;         while (__hip_atomic_load(bar + 64 * 34, __ATOMIC_RELAXED, __HIP_MEMORY_SCOPE_AGENT) < k) __builtin_amdgcn_s_sleep(2);
;         __builtin_amdgcn_fence(__ATOMIC_ACQUIRE, "agent");
;         asm volatile("s_waitcnt vmcnt(0)" ::: "memory");
.LBB0_115:
	s_sleep 0
	global_load_dword v2, v1, s[4:5] sc1
	s_waitcnt vmcnt(0)
	v_cmp_ge_u32_e32 vcc, v2, v0
	s_or_b64 s[8:9], vcc, s[8:9]
	s_andn2_b64 exec, exec, s[8:9]
	s_cbranch_execnz .LBB0_115

; DI void grid_barrier(int wv, unsigned* bar_, unsigned k, LAS unsigned* stash) {
;     ...
;         while (__hip_atomic_load(bar + 64 * 34, __ATOMIC_RELAXED, __HIP_MEMORY_SCOPE_AGENT) < k) __builtin_amdgcn_s_sleep(2);
;         __builtin_amdgcn_fence(__ATOMIC_ACQUIRE, "agent");
;         asm volatile("s_waitcnt vmcnt(0)" ::: "memory");
.LBB0_165:
	s_sleep 0
	global_load_dword v0, v1, s[4:5] sc1
	s_waitcnt vmcnt(0)
	v_cmp_ge_u32_e32 vcc, v0, v167
	s_or_b64 s[8:9], vcc, s[8:9]
	s_andn2_b64 exec, exec, s[8:9]
	s_cbranch_execnz .LBB0_165

; DI void grid_barrier(int wv, unsigned* bar_, unsigned k, LAS unsigned* stash) {
;     ...
;         while (__hip_atomic_load(bar + 64 * 34, __ATOMIC_RELAXED, __HIP_MEMORY_SCOPE_AGENT) < k) __builtin_amdgcn_s_sleep(2);
;         __builtin_amdgcn_fence(__ATOMIC_ACQUIRE, "agent");
;         asm volatile("s_waitcnt vmcnt(0)" ::: "memory");
.LBB0_507:
	s_sleep 0
	global_load_dword v2, v1, s[6:7] sc1
	s_waitcnt vmcnt(0)
	v_cmp_ge_u32_e32 vcc, v2, v0
	s_or_b64 s[22:23], vcc, s[22:23]
	s_andn2_b64 exec, exec, s[22:23]
	s_cbranch_execnz .LBB0_507
